# grid barrier: waiters poll the cross-XCD arrival counter itself (no separate release word, no per-XCD generation word): one more hop off each barrier
# baseline (speedup 1.0000x reference)
; __device__ __forceinline__ unsigned xb_ld(unsigned* p)              { return __hip_atomic_load(p, __ATOMIC_RELAXED, __HIP_MEMORY_SCOPE_AGENT); }
; __device__ __forceinline__ unsigned xb_add(unsigned* p, unsigned v) { return __hip_atomic_fetch_add(p, v, __ATOMIC_RELAXED, __HIP_MEMORY_SCOPE_AGENT); }
; #define XB_SPIN(cond, bar) do { unsigned _sp = 0; while (cond) { __builtin_amdgcn_s_sleep(1); \
;     if ((++_sp & 255u) == 0u) { if (xb_ld(&(bar)[XB_TMO])) break; if (_sp > XB_SPIN_CAP) { atomicAdd(&(bar)[XB_TMO], 1u); break; } } } } while (0)
; __device__ __forceinline__ void xcd_barrier(const XcdBarrier& b) {
;     ...
;         const unsigned old = xb_add(&bar[XB_XSUB(b.x)], 1u);
;         const unsigned gen = old / nloc;
;         if (old + 1u == (gen + 1u) * nloc) {
;     ...
;             XB_SPIN(xb_ld(&bar[XB_XGEN(b.x)]) == gen, bar);
.LBB0_366:
	s_or_b64 exec, exec, s[2:3]
	v_cvt_f32_u32_e32 v5, v3
	s_waitcnt vmcnt(0)
	v_readfirstlane_b32 s2, v4
	v_sub_u32_e32 v4, 0, v3
	v_rcp_iflag_f32_e32 v5, v5
	v_add_u32_e32 v6, s2, v0
	v_mul_f32_e32 v5, 0x4f7ffffe, v5
	v_cvt_u32_f32_e32 v5, v5
	v_mul_lo_u32 v0, v4, v5
	v_mul_hi_u32 v0, v5, v0
	v_add_u32_e32 v0, v5, v0
	v_mul_hi_u32 v0, v6, v0
	v_mul_lo_u32 v4, v0, v3
	v_sub_u32_e32 v4, v6, v4
	v_add_u32_e32 v5, 1, v0
	v_cmp_ge_u32_e32 vcc, v4, v3
	s_nop 1
	v_cndmask_b32_e32 v0, v0, v5, vcc
	v_sub_u32_e32 v5, v4, v3
	v_cndmask_b32_e32 v4, v4, v5, vcc
	v_add_u32_e32 v5, 1, v0
	v_cmp_ge_u32_e32 vcc, v4, v3
	v_add_u32_e32 v4, 1, v6
	s_nop 0
	v_cndmask_b32_e32 v0, v0, v5, vcc
	v_mul_lo_u32 v5, v3, v0
	v_add_u32_e32 v3, v5, v3
	v_cmp_ne_u32_e32 vcc, v4, v3
	s_and_saveexec_b64 s[2:3], vcc
	s_xor_b64 s[2:3], exec, s[2:3]
	s_cbranch_execz .LBB0_380
	v_readlane_b32 s6, v251, 62
	v_readlane_b32 s7, v251, 63
	s_waitcnt lgkmcnt(0)
	v_add_u32_e32 v3, 1, v0
	v_mul_lo_u32 v3, v3, v2
	s_nop 3
	global_load_dword v2, v1, s[6:7] sc1
	s_waitcnt vmcnt(0)
	v_cmp_lt_u32_e32 vcc, v2, v3
	s_and_saveexec_b64 s[14:15], vcc
	s_cbranch_execz .LBB0_379
	s_mov_b32 s26, 1
	s_mov_b64 s[16:17], 0
	s_branch .LBB0_370

; __device__ __forceinline__ unsigned xb_ld(unsigned* p)              { return __hip_atomic_load(p, __ATOMIC_RELAXED, __HIP_MEMORY_SCOPE_AGENT); }
; #define XB_SPIN(cond, bar) do { unsigned _sp = 0; while (cond) { __builtin_amdgcn_s_sleep(1); \
;     if ((++_sp & 255u) == 0u) { if (xb_ld(&(bar)[XB_TMO])) break; if (_sp > XB_SPIN_CAP) { atomicAdd(&(bar)[XB_TMO], 1u); break; } } } } while (0)
; __device__ __forceinline__ void xcd_barrier(const XcdBarrier& b) {
;     ...
;             XB_SPIN(xb_ld(&bar[XB_XGEN(b.x)]) == gen, bar);
.LBB0_372:
	v_readlane_b32 s6, v251, 62
	v_readlane_b32 s7, v251, 63
	s_add_i32 s26, s26, 1
	s_mov_b64 s[28:29], -1
	s_nop 2
	global_load_dword v2, v1, s[6:7] sc1
	s_waitcnt vmcnt(0)
	v_cmp_ge_u32_e32 vcc, v2, v3
	s_orn2_b64 s[24:25], vcc, exec
	s_branch .LBB0_369

; __device__ __forceinline__ unsigned xb_ld(unsigned* p)              { return __hip_atomic_load(p, __ATOMIC_RELAXED, __HIP_MEMORY_SCOPE_AGENT); }
; __device__ __forceinline__ unsigned xb_add(unsigned* p, unsigned v) { return __hip_atomic_fetch_add(p, v, __ATOMIC_RELAXED, __HIP_MEMORY_SCOPE_AGENT); }
; #define XB_SPIN(cond, bar) do { unsigned _sp = 0; while (cond) { __builtin_amdgcn_s_sleep(1); \
;     if ((++_sp & 255u) == 0u) { if (xb_ld(&(bar)[XB_TMO])) break; if (_sp > XB_SPIN_CAP) { atomicAdd(&(bar)[XB_TMO], 1u); break; } } } } while (0)
; __device__ __forceinline__ void xcd_barrier(const XcdBarrier& b) {
;     ...
;             const unsigned og = xb_add(&bar[XB_TOP], 1u);
;             const unsigned tg = og / nx;
;             if (og + 1u == (tg + 1u) * nx) xb_add(&bar[XB_TOPGEN], 1u);
;             else XB_SPIN(xb_ld(&bar[XB_TOPGEN]) == tg, bar);
.LBB0_383:
	s_or_b64 exec, exec, s[14:15]
	s_waitcnt vmcnt(0)
	v_readfirstlane_b32 s2, v3
	v_sub_u32_e32 v4, 0, v2
	s_mov_b64 s[14:15], 0
	v_add_u32_e32 v3, s2, v0
	v_cvt_f32_u32_e32 v0, v2
	v_readlane_b32 s2, v252, 0
	v_readlane_b32 s3, v252, 1
	v_rcp_iflag_f32_e32 v0, v0
	s_nop 0
	v_mul_f32_e32 v0, 0x4f7ffffe, v0
	v_cvt_u32_f32_e32 v0, v0
	v_mul_lo_u32 v4, v4, v0
	v_mul_hi_u32 v4, v0, v4
	v_add_u32_e32 v0, v0, v4
	v_mul_hi_u32 v0, v3, v0
	v_mul_lo_u32 v4, v0, v2
	v_sub_u32_e32 v4, v3, v4
	v_cmp_ge_u32_e32 vcc, v4, v2
	v_add_u32_e32 v5, 1, v0
	v_add_u32_e32 v3, 1, v3
	v_cndmask_b32_e32 v0, v0, v5, vcc
	v_sub_u32_e32 v5, v4, v2
	v_cndmask_b32_e32 v4, v4, v5, vcc
	v_cmp_ge_u32_e32 vcc, v4, v2
	v_add_u32_e32 v4, 1, v0
	s_nop 0
	v_cndmask_b32_e32 v0, v0, v4, vcc
	v_mul_lo_u32 v4, v2, v0
	v_add_u32_e32 v2, v4, v2
	v_cmp_ne_u32_e32 vcc, v3, v2
	v_mov_b32_e32 v5, v2
	v_mov_b64_e32 v[2:3], s[2:3]
	s_and_saveexec_b64 s[2:3], vcc
	s_cbranch_execz .LBB0_395
	v_readlane_b32 s6, v251, 62
	v_readlane_b32 s7, v251, 63
	s_mov_b64 s[16:17], 0
	s_nop 3
	global_load_dword v2, v1, s[6:7] sc1
	s_waitcnt vmcnt(0)
	v_cmp_lt_u32_e32 vcc, v2, v5
	s_and_saveexec_b64 s[14:15], vcc
	s_cbranch_execz .LBB0_394
	s_mov_b32 s26, 1
	s_branch .LBB0_387

; __device__ __forceinline__ unsigned xb_ld(unsigned* p)              { return __hip_atomic_load(p, __ATOMIC_RELAXED, __HIP_MEMORY_SCOPE_AGENT); }
; #define XB_SPIN(cond, bar) do { unsigned _sp = 0; while (cond) { __builtin_amdgcn_s_sleep(1); \
;     if ((++_sp & 255u) == 0u) { if (xb_ld(&(bar)[XB_TMO])) break; if (_sp > XB_SPIN_CAP) { atomicAdd(&(bar)[XB_TMO], 1u); break; } } } } while (0)
; __device__ __forceinline__ void xcd_barrier(const XcdBarrier& b) {
;     ...
;             else XB_SPIN(xb_ld(&bar[XB_TOPGEN]) == tg, bar);
.LBB0_389:
	v_readlane_b32 s6, v251, 62
	v_readlane_b32 s7, v251, 63
	s_add_i32 s26, s26, 1
	s_mov_b64 s[28:29], -1
	s_nop 2
	global_load_dword v2, v1, s[6:7] sc1
	s_waitcnt vmcnt(0)
	v_cmp_ge_u32_e32 vcc, v2, v5
	s_orn2_b64 s[24:25], vcc, exec
	s_branch .LBB0_386

; __device__ __forceinline__ unsigned xb_add(unsigned* p, unsigned v) { return __hip_atomic_fetch_add(p, v, __ATOMIC_RELAXED, __HIP_MEMORY_SCOPE_AGENT); }
; __device__ __forceinline__ void xcd_barrier(const XcdBarrier& b) {
;     ...
;             __builtin_amdgcn_fence(__ATOMIC_ACQUIRE, "agent");
;             xb_add(&bar[XB_XGEN(b.x)], 1u);
.LBB0_397:
	s_or_b64 exec, exec, s[2:3]
	s_mov_b64 s[2:3], exec
	v_mbcnt_lo_u32_b32 v0, s2, 0
	v_mbcnt_hi_u32_b32 v0, s3, v0
	v_cmp_eq_u32_e32 vcc, 0, v0
	s_waitcnt vmcnt(0)
	buffer_inv sc1
	s_and_saveexec_b64 s[14:15], vcc
	s_cbranch_execz .LBB0_399
	s_bcnt1_i32_b64 s2, s[2:3]
	v_mov_b32_e32 v0, s2
	v_readlane_b32 s2, v251, 60
	v_readlane_b32 s3, v251, 61
	s_nop 4
.LBB0_399:
	s_or_b64 exec, exec, s[14:15]
	s_waitcnt vmcnt(0)

; __device__ __forceinline__ unsigned xb_add(unsigned* p, unsigned v) { return __hip_atomic_fetch_add(p, v, __ATOMIC_RELAXED, __HIP_MEMORY_SCOPE_AGENT); }
; __device__ __forceinline__ void xcd_barrier(const XcdBarrier& b) {
;     ...
;             __builtin_amdgcn_fence(__ATOMIC_ACQUIRE, "agent");
;             xb_add(&bar[XB_XGEN(b.x)], 1u);
.LBB0_467:
	s_or_b64 exec, exec, s[2:3]
	s_mov_b64 s[2:3], exec
	v_mbcnt_lo_u32_b32 v0, s2, 0
	v_mbcnt_hi_u32_b32 v0, s3, v0
	v_cmp_eq_u32_e32 vcc, 0, v0
	s_waitcnt vmcnt(0)
	buffer_inv sc1
	s_and_saveexec_b64 s[14:15], vcc
	s_cbranch_execz .LBB0_469
	s_bcnt1_i32_b64 s2, s[2:3]
	v_mov_b32_e32 v0, s2
	v_readlane_b32 s2, v251, 60
	v_readlane_b32 s3, v251, 61
	s_nop 4
.LBB0_469:
	s_or_b64 exec, exec, s[14:15]
	s_waitcnt vmcnt(0)

; __device__ __forceinline__ unsigned xb_ld(unsigned* p)              { return __hip_atomic_load(p, __ATOMIC_RELAXED, __HIP_MEMORY_SCOPE_AGENT); }
; __device__ __forceinline__ unsigned xb_add(unsigned* p, unsigned v) { return __hip_atomic_fetch_add(p, v, __ATOMIC_RELAXED, __HIP_MEMORY_SCOPE_AGENT); }
; #define XB_SPIN(cond, bar) do { unsigned _sp = 0; while (cond) { __builtin_amdgcn_s_sleep(1); \
;     if ((++_sp & 255u) == 0u) { if (xb_ld(&(bar)[XB_TMO])) break; if (_sp > XB_SPIN_CAP) { atomicAdd(&(bar)[XB_TMO], 1u); break; } } } } while (0)
; __device__ __forceinline__ void xcd_barrier(const XcdBarrier& b) {
;     ...
;         const unsigned old = xb_add(&bar[XB_XSUB(b.x)], 1u);
;         const unsigned gen = old / nloc;
;         if (old + 1u == (gen + 1u) * nloc) {
;     ...
;             XB_SPIN(xb_ld(&bar[XB_XGEN(b.x)]) == gen, bar);
.LBB0_1816:
	s_or_b64 exec, exec, s[2:3]
	v_cvt_f32_u32_e32 v5, v3
	s_waitcnt vmcnt(0)
	v_readfirstlane_b32 s2, v4
	v_sub_u32_e32 v4, 0, v3
	v_rcp_iflag_f32_e32 v5, v5
	v_add_u32_e32 v6, s2, v0
	v_mul_f32_e32 v5, 0x4f7ffffe, v5
	v_cvt_u32_f32_e32 v5, v5
	v_mul_lo_u32 v0, v4, v5
	v_mul_hi_u32 v0, v5, v0
	v_add_u32_e32 v0, v5, v0
	v_mul_hi_u32 v0, v6, v0
	v_mul_lo_u32 v4, v0, v3
	v_sub_u32_e32 v4, v6, v4
	v_add_u32_e32 v5, 1, v0
	v_cmp_ge_u32_e32 vcc, v4, v3
	s_nop 1
	v_cndmask_b32_e32 v0, v0, v5, vcc
	v_sub_u32_e32 v5, v4, v3
	v_cndmask_b32_e32 v4, v4, v5, vcc
	v_add_u32_e32 v5, 1, v0
	v_cmp_ge_u32_e32 vcc, v4, v3
	v_add_u32_e32 v4, 1, v6
	s_nop 0
	v_cndmask_b32_e32 v0, v0, v5, vcc
	v_mul_lo_u32 v5, v3, v0
	v_add_u32_e32 v3, v5, v3
	v_cmp_ne_u32_e32 vcc, v4, v3
	s_and_saveexec_b64 s[2:3], vcc
	s_xor_b64 s[2:3], exec, s[2:3]
	s_cbranch_execz .LBB0_1830
	v_readlane_b32 s4, v251, 62
	v_readlane_b32 s5, v251, 63
	s_waitcnt lgkmcnt(0)
	v_add_u32_e32 v3, 1, v0
	v_mul_lo_u32 v3, v3, v2
	s_nop 3
	global_load_dword v2, v1, s[4:5] sc1
	s_waitcnt vmcnt(0)
	v_cmp_lt_u32_e32 vcc, v2, v3
	s_and_saveexec_b64 s[14:15], vcc
	s_cbranch_execz .LBB0_1829
	s_mov_b32 s4, 1
	s_mov_b64 s[16:17], 0
	s_branch .LBB0_1820

; __device__ __forceinline__ unsigned xb_ld(unsigned* p)              { return __hip_atomic_load(p, __ATOMIC_RELAXED, __HIP_MEMORY_SCOPE_AGENT); }
; #define XB_SPIN(cond, bar) do { unsigned _sp = 0; while (cond) { __builtin_amdgcn_s_sleep(1); \
;     if ((++_sp & 255u) == 0u) { if (xb_ld(&(bar)[XB_TMO])) break; if (_sp > XB_SPIN_CAP) { atomicAdd(&(bar)[XB_TMO], 1u); break; } } } } while (0)
; __device__ __forceinline__ void xcd_barrier(const XcdBarrier& b) {
;     ...
;             XB_SPIN(xb_ld(&bar[XB_XGEN(b.x)]) == gen, bar);
.LBB0_1822:
	v_readlane_b32 s6, v251, 62
	v_readlane_b32 s7, v251, 63
	s_add_i32 s4, s4, 1
	s_mov_b64 s[28:29], -1
	s_nop 2
	global_load_dword v2, v1, s[6:7] sc1
	s_waitcnt vmcnt(0)
	v_cmp_ge_u32_e32 vcc, v2, v3
	s_orn2_b64 s[24:25], vcc, exec
	s_branch .LBB0_1819

; __device__ __forceinline__ unsigned xb_ld(unsigned* p)              { return __hip_atomic_load(p, __ATOMIC_RELAXED, __HIP_MEMORY_SCOPE_AGENT); }
; __device__ __forceinline__ unsigned xb_add(unsigned* p, unsigned v) { return __hip_atomic_fetch_add(p, v, __ATOMIC_RELAXED, __HIP_MEMORY_SCOPE_AGENT); }
; #define XB_SPIN(cond, bar) do { unsigned _sp = 0; while (cond) { __builtin_amdgcn_s_sleep(1); \
;     if ((++_sp & 255u) == 0u) { if (xb_ld(&(bar)[XB_TMO])) break; if (_sp > XB_SPIN_CAP) { atomicAdd(&(bar)[XB_TMO], 1u); break; } } } } while (0)
; __device__ __forceinline__ void xcd_barrier(const XcdBarrier& b) {
;     ...
;             const unsigned og = xb_add(&bar[XB_TOP], 1u);
;             const unsigned tg = og / nx;
;             if (og + 1u == (tg + 1u) * nx) xb_add(&bar[XB_TOPGEN], 1u);
;             else XB_SPIN(xb_ld(&bar[XB_TOPGEN]) == tg, bar);
.LBB0_1833:
	s_or_b64 exec, exec, s[14:15]
	s_waitcnt vmcnt(0)
	v_readfirstlane_b32 s2, v3
	v_sub_u32_e32 v4, 0, v2
	s_mov_b64 s[14:15], 0
	v_add_u32_e32 v3, s2, v0
	v_cvt_f32_u32_e32 v0, v2
	v_readlane_b32 s2, v252, 0
	v_readlane_b32 s3, v252, 1
	v_rcp_iflag_f32_e32 v0, v0
	s_nop 0
	v_mul_f32_e32 v0, 0x4f7ffffe, v0
	v_cvt_u32_f32_e32 v0, v0
	v_mul_lo_u32 v4, v4, v0
	v_mul_hi_u32 v4, v0, v4
	v_add_u32_e32 v0, v0, v4
	v_mul_hi_u32 v0, v3, v0
	v_mul_lo_u32 v4, v0, v2
	v_sub_u32_e32 v4, v3, v4
	v_cmp_ge_u32_e32 vcc, v4, v2
	v_add_u32_e32 v5, 1, v0
	v_add_u32_e32 v3, 1, v3
	v_cndmask_b32_e32 v0, v0, v5, vcc
	v_sub_u32_e32 v5, v4, v2
	v_cndmask_b32_e32 v4, v4, v5, vcc
	v_cmp_ge_u32_e32 vcc, v4, v2
	v_add_u32_e32 v4, 1, v0
	s_nop 0
	v_cndmask_b32_e32 v0, v0, v4, vcc
	v_mul_lo_u32 v4, v2, v0
	v_add_u32_e32 v2, v4, v2
	v_cmp_ne_u32_e32 vcc, v3, v2
	v_mov_b32_e32 v5, v2
	v_mov_b64_e32 v[2:3], s[2:3]
	s_and_saveexec_b64 s[2:3], vcc
	s_cbranch_execz .LBB0_1845
	v_readlane_b32 s4, v251, 62
	v_readlane_b32 s5, v251, 63
	s_mov_b64 s[16:17], 0
	s_nop 3
	global_load_dword v2, v1, s[4:5] sc1
	s_waitcnt vmcnt(0)
	v_cmp_lt_u32_e32 vcc, v2, v5
	s_and_saveexec_b64 s[14:15], vcc
	s_cbranch_execz .LBB0_1844
	s_mov_b32 s4, 1
	s_branch .LBB0_1837

; __device__ __forceinline__ unsigned xb_ld(unsigned* p)              { return __hip_atomic_load(p, __ATOMIC_RELAXED, __HIP_MEMORY_SCOPE_AGENT); }
; #define XB_SPIN(cond, bar) do { unsigned _sp = 0; while (cond) { __builtin_amdgcn_s_sleep(1); \
;     if ((++_sp & 255u) == 0u) { if (xb_ld(&(bar)[XB_TMO])) break; if (_sp > XB_SPIN_CAP) { atomicAdd(&(bar)[XB_TMO], 1u); break; } } } } while (0)
; __device__ __forceinline__ void xcd_barrier(const XcdBarrier& b) {
;     ...
;             else XB_SPIN(xb_ld(&bar[XB_TOPGEN]) == tg, bar);
.LBB0_1839:
	v_readlane_b32 s6, v251, 62
	v_readlane_b32 s7, v251, 63
	s_add_i32 s4, s4, 1
	s_mov_b64 s[28:29], -1
	s_nop 2
	global_load_dword v2, v1, s[6:7] sc1
	s_waitcnt vmcnt(0)
	v_cmp_ge_u32_e32 vcc, v2, v5
	s_orn2_b64 s[24:25], vcc, exec
	s_branch .LBB0_1836

; __device__ __forceinline__ unsigned xb_add(unsigned* p, unsigned v) { return __hip_atomic_fetch_add(p, v, __ATOMIC_RELAXED, __HIP_MEMORY_SCOPE_AGENT); }
; __device__ __forceinline__ void xcd_barrier(const XcdBarrier& b) {
;     ...
;             __builtin_amdgcn_fence(__ATOMIC_ACQUIRE, "agent");
;             xb_add(&bar[XB_XGEN(b.x)], 1u);
.LBB0_1847:
	s_or_b64 exec, exec, s[2:3]
	s_mov_b64 s[2:3], exec
	v_mbcnt_lo_u32_b32 v0, s2, 0
	v_mbcnt_hi_u32_b32 v0, s3, v0
	v_cmp_eq_u32_e32 vcc, 0, v0
	s_waitcnt vmcnt(0)
	buffer_inv sc1
	s_and_saveexec_b64 s[14:15], vcc
	s_cbranch_execz .LBB0_1849
	s_bcnt1_i32_b64 s2, s[2:3]
	v_mov_b32_e32 v0, s2
	v_readlane_b32 s2, v251, 60
	v_readlane_b32 s3, v251, 61
	s_nop 4
.LBB0_1849:
	s_or_b64 exec, exec, s[14:15]
	s_waitcnt vmcnt(0)

; __device__ __forceinline__ unsigned xb_ld(unsigned* p)              { return __hip_atomic_load(p, __ATOMIC_RELAXED, __HIP_MEMORY_SCOPE_AGENT); }
; __device__ __forceinline__ unsigned xb_add(unsigned* p, unsigned v) { return __hip_atomic_fetch_add(p, v, __ATOMIC_RELAXED, __HIP_MEMORY_SCOPE_AGENT); }
; #define XB_SPIN(cond, bar) do { unsigned _sp = 0; while (cond) { __builtin_amdgcn_s_sleep(1); \
;     if ((++_sp & 255u) == 0u) { if (xb_ld(&(bar)[XB_TMO])) break; if (_sp > XB_SPIN_CAP) { atomicAdd(&(bar)[XB_TMO], 1u); break; } } } } while (0)
; __device__ __forceinline__ void xcd_barrier(const XcdBarrier& b) {
;     ...
;         const unsigned old = xb_add(&bar[XB_XSUB(b.x)], 1u);
;         const unsigned gen = old / nloc;
;         if (old + 1u == (gen + 1u) * nloc) {
;     ...
;             XB_SPIN(xb_ld(&bar[XB_XGEN(b.x)]) == gen, bar);
.LBB0_2125:
	s_or_b64 exec, exec, s[2:3]
	v_cvt_f32_u32_e32 v5, v3
	s_waitcnt vmcnt(0)
	v_readfirstlane_b32 s2, v4
	v_sub_u32_e32 v4, 0, v3
	v_rcp_iflag_f32_e32 v5, v5
	v_add_u32_e32 v6, s2, v0
	v_mul_f32_e32 v5, 0x4f7ffffe, v5
	v_cvt_u32_f32_e32 v5, v5
	v_mul_lo_u32 v0, v4, v5
	v_mul_hi_u32 v0, v5, v0
	v_add_u32_e32 v0, v5, v0
	v_mul_hi_u32 v0, v6, v0
	v_mul_lo_u32 v4, v0, v3
	v_sub_u32_e32 v4, v6, v4
	v_add_u32_e32 v5, 1, v0
	v_cmp_ge_u32_e32 vcc, v4, v3
	s_nop 1
	v_cndmask_b32_e32 v0, v0, v5, vcc
	v_sub_u32_e32 v5, v4, v3
	v_cndmask_b32_e32 v4, v4, v5, vcc
	v_add_u32_e32 v5, 1, v0
	v_cmp_ge_u32_e32 vcc, v4, v3
	v_add_u32_e32 v4, 1, v6
	s_nop 0
	v_cndmask_b32_e32 v0, v0, v5, vcc
	v_mul_lo_u32 v5, v3, v0
	v_add_u32_e32 v3, v5, v3
	v_cmp_ne_u32_e32 vcc, v4, v3
	s_and_saveexec_b64 s[2:3], vcc
	s_xor_b64 s[2:3], exec, s[2:3]
	s_cbranch_execz .LBB0_2139
	v_readlane_b32 s4, v251, 62
	v_readlane_b32 s5, v251, 63
	s_waitcnt lgkmcnt(0)
	v_add_u32_e32 v3, 1, v0
	v_mul_lo_u32 v3, v3, v2
	s_nop 3
	global_load_dword v2, v1, s[4:5] sc1
	s_waitcnt vmcnt(0)
	v_cmp_lt_u32_e32 vcc, v2, v3
	s_and_saveexec_b64 s[8:9], vcc
	s_cbranch_execz .LBB0_2138
	s_mov_b32 s4, 1
	s_mov_b64 s[10:11], 0
	s_branch .LBB0_2129

; __device__ __forceinline__ unsigned xb_ld(unsigned* p)              { return __hip_atomic_load(p, __ATOMIC_RELAXED, __HIP_MEMORY_SCOPE_AGENT); }
; #define XB_SPIN(cond, bar) do { unsigned _sp = 0; while (cond) { __builtin_amdgcn_s_sleep(1); \
;     if ((++_sp & 255u) == 0u) { if (xb_ld(&(bar)[XB_TMO])) break; if (_sp > XB_SPIN_CAP) { atomicAdd(&(bar)[XB_TMO], 1u); break; } } } } while (0)
; __device__ __forceinline__ void xcd_barrier(const XcdBarrier& b) {
;     ...
;             XB_SPIN(xb_ld(&bar[XB_XGEN(b.x)]) == gen, bar);
.LBB0_2131:
	v_readlane_b32 s6, v251, 62
	v_readlane_b32 s7, v251, 63
	s_add_i32 s4, s4, 1
	s_mov_b64 s[16:17], -1
	s_nop 2
	global_load_dword v2, v1, s[6:7] sc1
	s_waitcnt vmcnt(0)
	v_cmp_ge_u32_e32 vcc, v2, v3
	s_orn2_b64 s[14:15], vcc, exec
	s_branch .LBB0_2128

; __device__ __forceinline__ unsigned xb_ld(unsigned* p)              { return __hip_atomic_load(p, __ATOMIC_RELAXED, __HIP_MEMORY_SCOPE_AGENT); }
; __device__ __forceinline__ unsigned xb_add(unsigned* p, unsigned v) { return __hip_atomic_fetch_add(p, v, __ATOMIC_RELAXED, __HIP_MEMORY_SCOPE_AGENT); }
; #define XB_SPIN(cond, bar) do { unsigned _sp = 0; while (cond) { __builtin_amdgcn_s_sleep(1); \
;     if ((++_sp & 255u) == 0u) { if (xb_ld(&(bar)[XB_TMO])) break; if (_sp > XB_SPIN_CAP) { atomicAdd(&(bar)[XB_TMO], 1u); break; } } } } while (0)
; __device__ __forceinline__ void xcd_barrier(const XcdBarrier& b) {
;     ...
;             const unsigned og = xb_add(&bar[XB_TOP], 1u);
;             const unsigned tg = og / nx;
;             if (og + 1u == (tg + 1u) * nx) xb_add(&bar[XB_TOPGEN], 1u);
;             else XB_SPIN(xb_ld(&bar[XB_TOPGEN]) == tg, bar);
.LBB0_2142:
	s_or_b64 exec, exec, s[8:9]
	s_waitcnt vmcnt(0)
	v_readfirstlane_b32 s2, v3
	v_sub_u32_e32 v4, 0, v2
	s_mov_b64 s[8:9], 0
	v_add_u32_e32 v3, s2, v0
	v_cvt_f32_u32_e32 v0, v2
	v_readlane_b32 s2, v252, 0
	v_readlane_b32 s3, v252, 1
	v_rcp_iflag_f32_e32 v0, v0
	s_nop 0
	v_mul_f32_e32 v0, 0x4f7ffffe, v0
	v_cvt_u32_f32_e32 v0, v0
	v_mul_lo_u32 v4, v4, v0
	v_mul_hi_u32 v4, v0, v4
	v_add_u32_e32 v0, v0, v4
	v_mul_hi_u32 v0, v3, v0
	v_mul_lo_u32 v4, v0, v2
	v_sub_u32_e32 v4, v3, v4
	v_cmp_ge_u32_e32 vcc, v4, v2
	v_add_u32_e32 v5, 1, v0
	v_add_u32_e32 v3, 1, v3
	v_cndmask_b32_e32 v0, v0, v5, vcc
	v_sub_u32_e32 v5, v4, v2
	v_cndmask_b32_e32 v4, v4, v5, vcc
	v_cmp_ge_u32_e32 vcc, v4, v2
	v_add_u32_e32 v4, 1, v0
	s_nop 0
	v_cndmask_b32_e32 v0, v0, v4, vcc
	v_mul_lo_u32 v4, v2, v0
	v_add_u32_e32 v2, v4, v2
	v_cmp_ne_u32_e32 vcc, v3, v2
	v_mov_b32_e32 v5, v2
	v_mov_b64_e32 v[2:3], s[2:3]
	s_and_saveexec_b64 s[2:3], vcc
	s_cbranch_execz .LBB0_2154
	v_readlane_b32 s4, v251, 62
	v_readlane_b32 s5, v251, 63
	s_mov_b64 s[10:11], 0
	s_nop 3
	global_load_dword v2, v1, s[4:5] sc1
	s_waitcnt vmcnt(0)
	v_cmp_lt_u32_e32 vcc, v2, v5
	s_and_saveexec_b64 s[8:9], vcc
	s_cbranch_execz .LBB0_2153
	s_mov_b32 s4, 1
	s_branch .LBB0_2146

; __device__ __forceinline__ unsigned xb_ld(unsigned* p)              { return __hip_atomic_load(p, __ATOMIC_RELAXED, __HIP_MEMORY_SCOPE_AGENT); }
; #define XB_SPIN(cond, bar) do { unsigned _sp = 0; while (cond) { __builtin_amdgcn_s_sleep(1); \
;     if ((++_sp & 255u) == 0u) { if (xb_ld(&(bar)[XB_TMO])) break; if (_sp > XB_SPIN_CAP) { atomicAdd(&(bar)[XB_TMO], 1u); break; } } } } while (0)
; __device__ __forceinline__ void xcd_barrier(const XcdBarrier& b) {
;     ...
;             else XB_SPIN(xb_ld(&bar[XB_TOPGEN]) == tg, bar);
.LBB0_2148:
	v_readlane_b32 s6, v251, 62
	v_readlane_b32 s7, v251, 63
	s_add_i32 s4, s4, 1
	s_mov_b64 s[16:17], -1
	s_nop 2
	global_load_dword v2, v1, s[6:7] sc1
	s_waitcnt vmcnt(0)
	v_cmp_ge_u32_e32 vcc, v2, v5
	s_orn2_b64 s[14:15], vcc, exec
	s_branch .LBB0_2145

; __device__ __forceinline__ unsigned xb_add(unsigned* p, unsigned v) { return __hip_atomic_fetch_add(p, v, __ATOMIC_RELAXED, __HIP_MEMORY_SCOPE_AGENT); }
; __device__ __forceinline__ void xcd_barrier(const XcdBarrier& b) {
;     ...
;             __builtin_amdgcn_fence(__ATOMIC_ACQUIRE, "agent");
;             xb_add(&bar[XB_XGEN(b.x)], 1u);
.LBB0_2156:
	s_or_b64 exec, exec, s[2:3]
	s_mov_b64 s[2:3], exec
	v_mbcnt_lo_u32_b32 v0, s2, 0
	v_mbcnt_hi_u32_b32 v0, s3, v0
	v_cmp_eq_u32_e32 vcc, 0, v0
	s_waitcnt vmcnt(0)
	buffer_inv sc1
	s_and_saveexec_b64 s[8:9], vcc
	s_cbranch_execz .LBB0_2158
	s_bcnt1_i32_b64 s2, s[2:3]
	v_mov_b32_e32 v0, s2
	v_readlane_b32 s2, v251, 60
	v_readlane_b32 s3, v251, 61
	s_nop 4
.LBB0_2158:
	s_or_b64 exec, exec, s[8:9]
	s_waitcnt vmcnt(0)

; __device__ __forceinline__ unsigned xb_ld(unsigned* p)              { return __hip_atomic_load(p, __ATOMIC_RELAXED, __HIP_MEMORY_SCOPE_AGENT); }
; __device__ __forceinline__ unsigned xb_add(unsigned* p, unsigned v) { return __hip_atomic_fetch_add(p, v, __ATOMIC_RELAXED, __HIP_MEMORY_SCOPE_AGENT); }
; #define XB_SPIN(cond, bar) do { unsigned _sp = 0; while (cond) { __builtin_amdgcn_s_sleep(1); \
;     if ((++_sp & 255u) == 0u) { if (xb_ld(&(bar)[XB_TMO])) break; if (_sp > XB_SPIN_CAP) { atomicAdd(&(bar)[XB_TMO], 1u); break; } } } } while (0)
; __device__ __forceinline__ void xcd_barrier(const XcdBarrier& b) {
;     ...
;         const unsigned old = xb_add(&bar[XB_XSUB(b.x)], 1u);
;         const unsigned gen = old / nloc;
;         if (old + 1u == (gen + 1u) * nloc) {
;     ...
;             XB_SPIN(xb_ld(&bar[XB_XGEN(b.x)]) == gen, bar);
.LBB0_2187:
	s_or_b64 exec, exec, s[2:3]
	v_cvt_f32_u32_e32 v5, v3
	s_waitcnt vmcnt(0)
	v_readfirstlane_b32 s2, v4
	v_sub_u32_e32 v4, 0, v3
	v_rcp_iflag_f32_e32 v5, v5
	v_add_u32_e32 v6, s2, v0
	v_mul_f32_e32 v5, 0x4f7ffffe, v5
	v_cvt_u32_f32_e32 v5, v5
	v_mul_lo_u32 v0, v4, v5
	v_mul_hi_u32 v0, v5, v0
	v_add_u32_e32 v0, v5, v0
	v_mul_hi_u32 v0, v6, v0
	v_mul_lo_u32 v4, v0, v3
	v_sub_u32_e32 v4, v6, v4
	v_add_u32_e32 v5, 1, v0
	v_cmp_ge_u32_e32 vcc, v4, v3
	s_nop 1
	v_cndmask_b32_e32 v0, v0, v5, vcc
	v_sub_u32_e32 v5, v4, v3
	v_cndmask_b32_e32 v4, v4, v5, vcc
	v_add_u32_e32 v5, 1, v0
	v_cmp_ge_u32_e32 vcc, v4, v3
	v_add_u32_e32 v4, 1, v6
	s_nop 0
	v_cndmask_b32_e32 v0, v0, v5, vcc
	v_mul_lo_u32 v5, v3, v0
	v_add_u32_e32 v3, v5, v3
	v_cmp_ne_u32_e32 vcc, v4, v3
	s_and_saveexec_b64 s[2:3], vcc
	s_xor_b64 s[2:3], exec, s[2:3]
	s_cbranch_execz .LBB0_2201
	v_readlane_b32 s4, v251, 62
	v_readlane_b32 s5, v251, 63
	s_waitcnt lgkmcnt(0)
	v_add_u32_e32 v3, 1, v0
	v_mul_lo_u32 v3, v3, v2
	s_nop 3
	global_load_dword v2, v1, s[4:5] sc1
	s_waitcnt vmcnt(0)
	v_cmp_lt_u32_e32 vcc, v2, v3
	s_and_saveexec_b64 s[6:7], vcc
	s_cbranch_execz .LBB0_2200
	s_mov_b32 s4, 1
	s_mov_b64 s[8:9], 0
	s_branch .LBB0_2191

; __device__ __forceinline__ unsigned xb_ld(unsigned* p)              { return __hip_atomic_load(p, __ATOMIC_RELAXED, __HIP_MEMORY_SCOPE_AGENT); }
; #define XB_SPIN(cond, bar) do { unsigned _sp = 0; while (cond) { __builtin_amdgcn_s_sleep(1); \
;     if ((++_sp & 255u) == 0u) { if (xb_ld(&(bar)[XB_TMO])) break; if (_sp > XB_SPIN_CAP) { atomicAdd(&(bar)[XB_TMO], 1u); break; } } } } while (0)
; __device__ __forceinline__ void xcd_barrier(const XcdBarrier& b) {
;     ...
;             XB_SPIN(xb_ld(&bar[XB_XGEN(b.x)]) == gen, bar);
.LBB0_2193:
	v_readlane_b32 s12, v251, 62
	v_readlane_b32 s13, v251, 63
	s_add_i32 s4, s4, 1
	s_mov_b64 s[14:15], -1
	s_nop 2
	global_load_dword v2, v1, s[12:13] sc1
	s_waitcnt vmcnt(0)
	v_cmp_ge_u32_e32 vcc, v2, v3
	s_orn2_b64 s[12:13], vcc, exec
	s_branch .LBB0_2190

; __device__ __forceinline__ unsigned xb_ld(unsigned* p)              { return __hip_atomic_load(p, __ATOMIC_RELAXED, __HIP_MEMORY_SCOPE_AGENT); }
; __device__ __forceinline__ unsigned xb_add(unsigned* p, unsigned v) { return __hip_atomic_fetch_add(p, v, __ATOMIC_RELAXED, __HIP_MEMORY_SCOPE_AGENT); }
; #define XB_SPIN(cond, bar) do { unsigned _sp = 0; while (cond) { __builtin_amdgcn_s_sleep(1); \
;     if ((++_sp & 255u) == 0u) { if (xb_ld(&(bar)[XB_TMO])) break; if (_sp > XB_SPIN_CAP) { atomicAdd(&(bar)[XB_TMO], 1u); break; } } } } while (0)
; __device__ __forceinline__ void xcd_barrier(const XcdBarrier& b) {
;     ...
;             const unsigned og = xb_add(&bar[XB_TOP], 1u);
;             const unsigned tg = og / nx;
;             if (og + 1u == (tg + 1u) * nx) xb_add(&bar[XB_TOPGEN], 1u);
;             else XB_SPIN(xb_ld(&bar[XB_TOPGEN]) == tg, bar);
.LBB0_2204:
	s_or_b64 exec, exec, s[6:7]
	s_waitcnt vmcnt(0)
	v_readfirstlane_b32 s2, v3
	v_sub_u32_e32 v4, 0, v2
	s_mov_b64 s[6:7], 0
	v_add_u32_e32 v3, s2, v0
	v_cvt_f32_u32_e32 v0, v2
	v_readlane_b32 s2, v252, 0
	v_readlane_b32 s3, v252, 1
	v_rcp_iflag_f32_e32 v0, v0
	s_nop 0
	v_mul_f32_e32 v0, 0x4f7ffffe, v0
	v_cvt_u32_f32_e32 v0, v0
	v_mul_lo_u32 v4, v4, v0
	v_mul_hi_u32 v4, v0, v4
	v_add_u32_e32 v0, v0, v4
	v_mul_hi_u32 v0, v3, v0
	v_mul_lo_u32 v4, v0, v2
	v_sub_u32_e32 v4, v3, v4
	v_cmp_ge_u32_e32 vcc, v4, v2
	v_add_u32_e32 v5, 1, v0
	v_add_u32_e32 v3, 1, v3
	v_cndmask_b32_e32 v0, v0, v5, vcc
	v_sub_u32_e32 v5, v4, v2
	v_cndmask_b32_e32 v4, v4, v5, vcc
	v_cmp_ge_u32_e32 vcc, v4, v2
	v_add_u32_e32 v4, 1, v0
	s_nop 0
	v_cndmask_b32_e32 v0, v0, v4, vcc
	v_mul_lo_u32 v4, v2, v0
	v_add_u32_e32 v2, v4, v2
	v_cmp_ne_u32_e32 vcc, v3, v2
	v_mov_b32_e32 v5, v2
	v_mov_b64_e32 v[2:3], s[2:3]
	s_and_saveexec_b64 s[2:3], vcc
	s_cbranch_execz .LBB0_2216
	v_readlane_b32 s4, v251, 62
	v_readlane_b32 s5, v251, 63
	s_mov_b64 s[8:9], 0
	s_nop 3
	global_load_dword v2, v1, s[4:5] sc1
	s_waitcnt vmcnt(0)
	v_cmp_lt_u32_e32 vcc, v2, v5
	s_and_saveexec_b64 s[6:7], vcc
	s_cbranch_execz .LBB0_2215
	s_mov_b32 s4, 1
	s_branch .LBB0_2208

; __device__ __forceinline__ unsigned xb_ld(unsigned* p)              { return __hip_atomic_load(p, __ATOMIC_RELAXED, __HIP_MEMORY_SCOPE_AGENT); }
; #define XB_SPIN(cond, bar) do { unsigned _sp = 0; while (cond) { __builtin_amdgcn_s_sleep(1); \
;     if ((++_sp & 255u) == 0u) { if (xb_ld(&(bar)[XB_TMO])) break; if (_sp > XB_SPIN_CAP) { atomicAdd(&(bar)[XB_TMO], 1u); break; } } } } while (0)
; __device__ __forceinline__ void xcd_barrier(const XcdBarrier& b) {
;     ...
;             else XB_SPIN(xb_ld(&bar[XB_TOPGEN]) == tg, bar);
.LBB0_2210:
	v_readlane_b32 s12, v251, 62
	v_readlane_b32 s13, v251, 63
	s_add_i32 s4, s4, 1
	s_mov_b64 s[14:15], -1
	s_nop 2
	global_load_dword v2, v1, s[12:13] sc1
	s_waitcnt vmcnt(0)
	v_cmp_ge_u32_e32 vcc, v2, v5
	s_orn2_b64 s[12:13], vcc, exec
	s_branch .LBB0_2207

; __device__ __forceinline__ unsigned xb_add(unsigned* p, unsigned v) { return __hip_atomic_fetch_add(p, v, __ATOMIC_RELAXED, __HIP_MEMORY_SCOPE_AGENT); }
; __device__ __forceinline__ void xcd_barrier(const XcdBarrier& b) {
;     ...
;             __builtin_amdgcn_fence(__ATOMIC_ACQUIRE, "agent");
;             xb_add(&bar[XB_XGEN(b.x)], 1u);
.LBB0_2218:
	s_or_b64 exec, exec, s[2:3]
	s_mov_b64 s[2:3], exec
	v_mbcnt_lo_u32_b32 v0, s2, 0
	v_mbcnt_hi_u32_b32 v0, s3, v0
	v_cmp_eq_u32_e32 vcc, 0, v0
	s_waitcnt vmcnt(0)
	buffer_inv sc1
	s_and_saveexec_b64 s[6:7], vcc
	s_cbranch_execz .LBB0_2220
	s_bcnt1_i32_b64 s2, s[2:3]
	v_mov_b32_e32 v0, s2
	v_readlane_b32 s2, v251, 60
	v_readlane_b32 s3, v251, 61
	s_nop 4
.LBB0_2220:
	s_or_b64 exec, exec, s[6:7]
	s_waitcnt vmcnt(0)

; __device__ __forceinline__ unsigned xb_ld(unsigned* p)              { return __hip_atomic_load(p, __ATOMIC_RELAXED, __HIP_MEMORY_SCOPE_AGENT); }
; __device__ __forceinline__ unsigned xb_add(unsigned* p, unsigned v) { return __hip_atomic_fetch_add(p, v, __ATOMIC_RELAXED, __HIP_MEMORY_SCOPE_AGENT); }
; #define XB_SPIN(cond, bar) do { unsigned _sp = 0; while (cond) { __builtin_amdgcn_s_sleep(1); \
;     if ((++_sp & 255u) == 0u) { if (xb_ld(&(bar)[XB_TMO])) break; if (_sp > XB_SPIN_CAP) { atomicAdd(&(bar)[XB_TMO], 1u); break; } } } } while (0)
; __device__ __forceinline__ void xcd_barrier(const XcdBarrier& b) {
;     ...
;         const unsigned old = xb_add(&bar[XB_XSUB(b.x)], 1u);
;         const unsigned gen = old / nloc;
;         if (old + 1u == (gen + 1u) * nloc) {
;     ...
;             XB_SPIN(xb_ld(&bar[XB_XGEN(b.x)]) == gen, bar);
.LBB0_2457:
	s_or_b64 exec, exec, s[2:3]
	v_cvt_f32_u32_e32 v5, v3
	s_waitcnt vmcnt(0)
	v_readfirstlane_b32 s2, v4
	v_sub_u32_e32 v4, 0, v3
	v_rcp_iflag_f32_e32 v5, v5
	v_add_u32_e32 v6, s2, v0
	v_mul_f32_e32 v5, 0x4f7ffffe, v5
	v_cvt_u32_f32_e32 v5, v5
	v_mul_lo_u32 v0, v4, v5
	v_mul_hi_u32 v0, v5, v0
	v_add_u32_e32 v0, v5, v0
	v_mul_hi_u32 v0, v6, v0
	v_mul_lo_u32 v4, v0, v3
	v_sub_u32_e32 v4, v6, v4
	v_add_u32_e32 v5, 1, v0
	v_cmp_ge_u32_e32 vcc, v4, v3
	s_nop 1
	v_cndmask_b32_e32 v0, v0, v5, vcc
	v_sub_u32_e32 v5, v4, v3
	v_cndmask_b32_e32 v4, v4, v5, vcc
	v_add_u32_e32 v5, 1, v0
	v_cmp_ge_u32_e32 vcc, v4, v3
	v_add_u32_e32 v4, 1, v6
	s_nop 0
	v_cndmask_b32_e32 v0, v0, v5, vcc
	v_mul_lo_u32 v5, v3, v0
	v_add_u32_e32 v3, v5, v3
	v_cmp_ne_u32_e32 vcc, v4, v3
	s_and_saveexec_b64 s[2:3], vcc
	s_xor_b64 s[2:3], exec, s[2:3]
	s_cbranch_execz .LBB0_2471
	v_readlane_b32 s6, v251, 62
	v_readlane_b32 s7, v251, 63
	s_waitcnt lgkmcnt(0)
	v_add_u32_e32 v3, 1, v0
	v_mul_lo_u32 v3, v3, v2
	s_nop 3
	global_load_dword v2, v1, s[6:7] sc1
	s_waitcnt vmcnt(0)
	v_cmp_lt_u32_e32 vcc, v2, v3
	s_and_saveexec_b64 s[6:7], vcc
	s_cbranch_execz .LBB0_2470
	s_mov_b32 s4, 1
	s_mov_b64 s[8:9], 0
	s_branch .LBB0_2461

; __device__ __forceinline__ unsigned xb_ld(unsigned* p)              { return __hip_atomic_load(p, __ATOMIC_RELAXED, __HIP_MEMORY_SCOPE_AGENT); }
; __device__ __forceinline__ unsigned xb_add(unsigned* p, unsigned v) { return __hip_atomic_fetch_add(p, v, __ATOMIC_RELAXED, __HIP_MEMORY_SCOPE_AGENT); }
; #define XB_SPIN(cond, bar) do { unsigned _sp = 0; while (cond) { __builtin_amdgcn_s_sleep(1); \
;     if ((++_sp & 255u) == 0u) { if (xb_ld(&(bar)[XB_TMO])) break; if (_sp > XB_SPIN_CAP) { atomicAdd(&(bar)[XB_TMO], 1u); break; } } } } while (0)
; __device__ __forceinline__ void xcd_barrier(const XcdBarrier& b) {
;     ...
;             const unsigned og = xb_add(&bar[XB_TOP], 1u);
;             const unsigned tg = og / nx;
;             if (og + 1u == (tg + 1u) * nx) xb_add(&bar[XB_TOPGEN], 1u);
;             else XB_SPIN(xb_ld(&bar[XB_TOPGEN]) == tg, bar);
.LBB0_2474:
	s_or_b64 exec, exec, s[6:7]
	s_waitcnt vmcnt(0)
	v_readfirstlane_b32 s2, v3
	v_sub_u32_e32 v4, 0, v2
	s_mov_b64 s[6:7], 0
	v_add_u32_e32 v3, s2, v0
	v_cvt_f32_u32_e32 v0, v2
	v_readlane_b32 s2, v252, 0
	v_readlane_b32 s3, v252, 1
	v_rcp_iflag_f32_e32 v0, v0
	s_nop 0
	v_mul_f32_e32 v0, 0x4f7ffffe, v0
	v_cvt_u32_f32_e32 v0, v0
	v_mul_lo_u32 v4, v4, v0
	v_mul_hi_u32 v4, v0, v4
	v_add_u32_e32 v0, v0, v4
	v_mul_hi_u32 v0, v3, v0
	v_mul_lo_u32 v4, v0, v2
	v_sub_u32_e32 v4, v3, v4
	v_cmp_ge_u32_e32 vcc, v4, v2
	v_add_u32_e32 v5, 1, v0
	v_add_u32_e32 v3, 1, v3
	v_cndmask_b32_e32 v0, v0, v5, vcc
	v_sub_u32_e32 v5, v4, v2
	v_cndmask_b32_e32 v4, v4, v5, vcc
	v_cmp_ge_u32_e32 vcc, v4, v2
	v_add_u32_e32 v4, 1, v0
	s_nop 0
	v_cndmask_b32_e32 v0, v0, v4, vcc
	v_mul_lo_u32 v4, v2, v0
	v_add_u32_e32 v2, v4, v2
	v_cmp_ne_u32_e32 vcc, v3, v2
	v_mov_b32_e32 v5, v2
	v_mov_b64_e32 v[2:3], s[2:3]
	s_and_saveexec_b64 s[2:3], vcc
	s_cbranch_execz .LBB0_2486
	v_readlane_b32 s6, v251, 62
	v_readlane_b32 s7, v251, 63
	s_mov_b64 s[8:9], 0
	s_nop 3
	global_load_dword v2, v1, s[6:7] sc1
	s_waitcnt vmcnt(0)
	v_cmp_lt_u32_e32 vcc, v2, v5
	s_and_saveexec_b64 s[6:7], vcc
	s_cbranch_execz .LBB0_2485
	s_mov_b32 s4, 1
	s_branch .LBB0_2478

; __device__ __forceinline__ unsigned xb_add(unsigned* p, unsigned v) { return __hip_atomic_fetch_add(p, v, __ATOMIC_RELAXED, __HIP_MEMORY_SCOPE_AGENT); }
; __device__ __forceinline__ void xcd_barrier(const XcdBarrier& b) {
;     ...
;             __builtin_amdgcn_fence(__ATOMIC_ACQUIRE, "agent");
;             xb_add(&bar[XB_XGEN(b.x)], 1u);
.LBB0_2488:
	s_or_b64 exec, exec, s[2:3]
	s_mov_b64 s[2:3], exec
	v_mbcnt_lo_u32_b32 v0, s2, 0
	v_mbcnt_hi_u32_b32 v0, s3, v0
	v_cmp_eq_u32_e32 vcc, 0, v0
	s_waitcnt vmcnt(0)
	buffer_inv sc1
	s_and_saveexec_b64 s[6:7], vcc
	s_cbranch_execz .LBB0_2490
	s_bcnt1_i32_b64 s2, s[2:3]
	v_mov_b32_e32 v0, s2
	v_readlane_b32 s2, v251, 60
	v_readlane_b32 s3, v251, 61
	s_nop 4
.LBB0_2490:
	s_or_b64 exec, exec, s[6:7]
	s_waitcnt vmcnt(0)

; __device__ __forceinline__ unsigned xb_add(unsigned* p, unsigned v) { return __hip_atomic_fetch_add(p, v, __ATOMIC_RELAXED, __HIP_MEMORY_SCOPE_AGENT); }
; __device__ __forceinline__ void xcd_barrier(const XcdBarrier& b) {
;     ...
;             __builtin_amdgcn_fence(__ATOMIC_ACQUIRE, "agent");
;             xb_add(&bar[XB_XGEN(b.x)], 1u);
.LBB0_2722:
	s_or_b64 exec, exec, s[2:3]
	s_mov_b64 s[2:3], exec
	v_mbcnt_lo_u32_b32 v0, s2, 0
	v_mbcnt_hi_u32_b32 v0, s3, v0
	v_cmp_eq_u32_e32 vcc, 0, v0
	s_waitcnt vmcnt(0)
	buffer_inv sc1
	s_and_saveexec_b64 s[6:7], vcc
	s_cbranch_execz .LBB0_2724
	s_bcnt1_i32_b64 s2, s[2:3]
	v_mov_b32_e32 v0, s2
	v_readlane_b32 s2, v251, 60
	v_readlane_b32 s3, v251, 61
	s_nop 4
.LBB0_2724:
	s_or_b64 exec, exec, s[6:7]
	s_waitcnt vmcnt(0)

; __device__ __forceinline__ unsigned xb_add(unsigned* p, unsigned v) { return __hip_atomic_fetch_add(p, v, __ATOMIC_RELAXED, __HIP_MEMORY_SCOPE_AGENT); }
; __device__ __forceinline__ void xcd_barrier(const XcdBarrier& b) {
;     ...
;             __builtin_amdgcn_fence(__ATOMIC_ACQUIRE, "agent");
;             xb_add(&bar[XB_XGEN(b.x)], 1u);
.LBB0_4674:
	s_or_b64 exec, exec, s[2:3]
	s_mov_b64 s[2:3], exec
	v_mbcnt_lo_u32_b32 v0, s2, 0
	v_mbcnt_hi_u32_b32 v0, s3, v0
	v_cmp_eq_u32_e32 vcc, 0, v0
	s_waitcnt vmcnt(0)
	buffer_inv sc1
	s_and_saveexec_b64 s[6:7], vcc
	s_cbranch_execz .LBB0_4676
	s_bcnt1_i32_b64 s2, s[2:3]
	v_mov_b32_e32 v0, s2
	v_readlane_b32 s2, v251, 60
	v_readlane_b32 s3, v251, 61
	s_nop 4
.LBB0_4676:
	s_or_b64 exec, exec, s[6:7]
	s_waitcnt vmcnt(0)

; __device__ __forceinline__ unsigned xb_add(unsigned* p, unsigned v) { return __hip_atomic_fetch_add(p, v, __ATOMIC_RELAXED, __HIP_MEMORY_SCOPE_AGENT); }
; __device__ __forceinline__ void xcd_barrier(const XcdBarrier& b) {
;     ...
;             __builtin_amdgcn_fence(__ATOMIC_ACQUIRE, "agent");
;             xb_add(&bar[XB_XGEN(b.x)], 1u);
.LBB0_4868:
	s_or_b64 exec, exec, s[2:3]
	s_mov_b64 s[2:3], exec
	v_mbcnt_lo_u32_b32 v0, s2, 0
	v_mbcnt_hi_u32_b32 v0, s3, v0
	v_cmp_eq_u32_e32 vcc, 0, v0
	s_waitcnt vmcnt(0)
	buffer_inv sc1
	s_and_saveexec_b64 s[6:7], vcc
	s_cbranch_execz .LBB0_4870
	s_bcnt1_i32_b64 s2, s[2:3]
	v_mov_b32_e32 v0, s2
	v_readlane_b32 s2, v251, 60
	v_readlane_b32 s3, v251, 61
	s_nop 4
.LBB0_4870:
	s_or_b64 exec, exec, s[6:7]
	s_waitcnt vmcnt(0)

; __device__ __forceinline__ unsigned xb_add(unsigned* p, unsigned v) { return __hip_atomic_fetch_add(p, v, __ATOMIC_RELAXED, __HIP_MEMORY_SCOPE_AGENT); }
; __device__ __forceinline__ void xcd_barrier(const XcdBarrier& b) {
;     ...
;             __builtin_amdgcn_fence(__ATOMIC_ACQUIRE, "agent");
;             xb_add(&bar[XB_XGEN(b.x)], 1u);
.LBB0_4996:
	s_bcnt1_i32_b64 s2, s[2:3]
	v_mov_b32_e32 v0, s2
	v_readlane_b32 s2, v251, 60
	v_readlane_b32 s3, v251, 61
	s_nop 4
	s_getpc_b64 s[98:99]
